# code placement: NA tile loop body shifted by 4 bytes
# speedup vs baseline: 1.0042x; 1.0042x over previous
.LBB0_389:
	global_load_dword v7, v[2:3], off
	s_mov_b64 s[8:9], 0x400
	v_add_u32_e32 v6, 0x100, v6
	v_lshl_add_u64 v[2:3], v[2:3], 0, s[8:9]
	s_movk_i32 s8, 0xd0
	v_cmp_lt_u32_e32 vcc, s8, v6
	s_or_b64 s[4:5], vcc, s[4:5]
	s_waitcnt vmcnt(0)
	v_mul_f32_e32 v7, 0x3fb8aa3b, v7
	ds_write_b32 v5, v7
	v_add_u32_e32 v5, 0x400, v5
	s_andn2_b64 exec, exec, s[4:5]
	s_cbranch_execnz .LBB0_389
	s_or_b64 exec, exec, s[4:5]
	s_bfe_u32 s30, s35, 0x50003
	s_and_b32 s4, s6, 32
	s_or_b32 s48, s4, s30
	v_med3_u32 v2, s48, 4, 60
	s_lshr_b32 s82, s7, 8
	v_readfirstlane_b32 s4, v2
	s_mul_i32 s6, s4, 0x58000
	s_lshl_b64 s[4:5], s[82:83], 12
	s_add_u32 s71, s4, 0x1000
	s_addc_u32 s49, s5, 0
	s_mul_i32 s4, s49, 0x2c00
	s_mul_hi_u32 s5, s71, 0x2c00
	s_add_i32 s5, s5, s4
	s_mul_i32 s4, s71, 0x2c00
	s_add_u32 s4, s38, s4
	s_addc_u32 s5, s39, s5
	s_add_u32 s8, s4, 0x1e74b200
	s_addc_u32 s9, s5, 0
	s_add_i32 s4, s6, 0xffea0000
	s_mov_b32 s5, s83
	s_lshl_b64 s[4:5], s[4:5], 1
	s_add_u32 s4, s8, s4
	s_addc_u32 s5, s9, s5
	s_bfe_u32 s31, s34, 0x10008
	s_lshl_b32 s10, s31, 5
	s_lshl_b32 s6, s82, 2
	s_or_b32 s10, s10, s30
	s_add_i32 s82, s6, s96
	v_med3_u32 v2, s10, 4, 60
	s_movk_i32 s10, 0x7c
	v_lshlrev_b32_e32 v152, 7, v0
	s_lshl_b64 s[6:7], s[82:83], 18
	v_mul_lo_u32 v5, v2, s10
	s_mul_i32 s10, s48, 0xb0000
	s_add_u32 s8, s8, s10
	v_ashrrev_i32_e32 v153, 31, v152
	s_addc_u32 s9, s9, 0
	v_lshlrev_b64 v[2:3], 1, v[152:153]
	v_lshlrev_b64 v[0:1], 15, v[0:1]
	v_lshl_add_u64 v[6:7], s[8:9], 0, v[2:3]
	v_lshl_add_u64 v[2:3], s[4:5], 0, v[2:3]
	s_mov_b64 s[4:5], 0x1000
	v_lshl_add_u64 v[0:1], v[0:1], 0, s[6:7]
	v_lshl_add_u64 v[156:157], v[2:3], 0, s[4:5]
	v_lshl_add_u64 v[0:1], v[0:1], 1, s[38:39]
	s_mov_b64 s[4:5], 0x11a04000
	v_lshl_add_u64 v[158:159], v[0:1], 0, s[4:5]
	s_mov_b64 s[4:5], 0x11e04000
	v_lshl_add_u64 v[160:161], v[0:1], 0, s[4:5]
	v_lshrrev_b32_e32 v0, 2, v167
	v_and_b32_e32 v1, 15, v167
	v_and_b32_e32 v26, 48, v0
	v_or_b32_e32 v172, v26, v1
	v_mul_u32_u24_e32 v10, 0x1600, v172
	v_and_b32_e32 v17, 3, v171
	v_lshlrev_b32_e32 v10, 1, v10
	v_mov_b32_e32 v11, v16
	v_lshl_add_u64 v[6:7], v[6:7], 0, v[10:11]
	v_lshlrev_b32_e32 v10, 4, v17
	v_or_b32_e32 v214, 48, v171
	v_lshl_add_u64 v[6:7], v[6:7], 0, v[10:11]
	v_lshlrev_b32_e32 v27, 3, v169
	global_load_dwordx4 v[50:53], v[6:7], off offset:192
	global_load_dwordx4 v[54:57], v[6:7], off offset:128
	global_load_dwordx4 v[58:61], v[6:7], off offset:64
	global_load_dwordx4 v[62:65], v[6:7], off
	v_mul_u32_u24_e32 v6, 0x1600, v214
	v_mov_b32_e32 v7, v16
	s_movk_i32 s6, 0x1600
	v_mov_b32_e32 v11, 0xfffea000
	v_and_b32_e32 v8, 0x78, v27
	v_lshlrev_b64 v[6:7], 1, v[6:7]
	v_mad_u32_u24 v18, v214, s6, v11
	v_mov_b32_e32 v19, v16
	v_lshl_add_u64 v[12:13], v[156:157], 0, v[6:7]
	v_lshlrev_b32_e32 v14, 1, v8
	v_mov_b32_e32 v15, v16
	v_lshlrev_b64 v[18:19], 1, v[18:19]
	v_lshl_add_u64 v[12:13], v[12:13], 0, v[14:15]
	v_lshl_add_u64 v[20:21], v[156:157], 0, v[18:19]
	v_mov_b32_e32 v11, 0xfffd4000
	v_lshl_add_u64 v[20:21], v[20:21], 0, v[14:15]
	global_load_dwordx4 v[66:69], v[12:13], off
	global_load_dwordx4 v[70:73], v[20:21], off
	v_mad_u32_u24 v12, v214, s6, v11
	v_mov_b32_e32 v13, v16
	v_lshlrev_b64 v[12:13], 1, v[12:13]
	v_mul_u32_u24_e32 v22, 0x1600, v171
	v_mov_b32_e32 v23, v16
	v_lshl_add_u64 v[20:21], v[156:157], 0, v[12:13]
	v_lshlrev_b64 v[22:23], 1, v[22:23]
	v_lshl_add_u64 v[6:7], v[2:3], 0, v[6:7]
	v_lshl_add_u64 v[20:21], v[20:21], 0, v[14:15]
	v_lshl_add_u64 v[24:25], v[156:157], 0, v[22:23]
	v_lshl_add_u64 v[6:7], v[6:7], 0, v[14:15]
	v_lshl_add_u64 v[18:19], v[2:3], 0, v[18:19]
	v_lshl_add_u64 v[24:25], v[24:25], 0, v[14:15]
	global_load_dwordx4 v[74:77], v[20:21], off
	global_load_dwordx4 v[78:81], v[24:25], off
	v_lshl_add_u64 v[18:19], v[18:19], 0, v[14:15]
	global_load_dwordx4 v[86:89], v[6:7], off offset:2048
	global_load_dwordx4 v[94:97], v[18:19], off offset:2048
	v_lshl_add_u64 v[6:7], v[2:3], 0, v[12:13]
	v_lshl_add_u64 v[154:155], v[2:3], 0, s[94:95]
	v_lshl_add_u64 v[6:7], v[6:7], 0, v[14:15]
	v_lshl_add_u64 v[2:3], v[2:3], 0, v[22:23]
	v_lshlrev_b32_e32 v12, 4, v1
	v_mov_b32_e32 v13, v16
	v_lshl_add_u64 v[2:3], v[2:3], 0, v[12:13]
	global_load_dwordx4 v[82:85], v[6:7], off offset:2048
	global_load_dwordx4 v[90:93], v[2:3], off offset:2048
	v_and_b32_e32 v23, 64, v191
	v_xor_b32_e32 v22, 16, v191
	v_add_u32_e32 v23, 64, v23
	v_cmp_lt_i32_e32 vcc, v22, v23
	v_add_u32_e32 v9, 0, v4
	v_or_b32_e32 v182, 16, v171
	v_cndmask_b32_e32 v22, v191, v22, vcc
	v_or_b32_e32 v183, 32, v171
	v_lshlrev_b32_e32 v173, 2, v17
	v_and_b32_e32 v15, 24, v27
	v_lshlrev_b32_e32 v178, 2, v22
	v_xor_b32_e32 v22, 32, v191
	v_bitop3_b32 v24, v17, v1, 4 bitop3:0x36
	v_bitop3_b32 v17, v17, v1, 8 bitop3:0x36
	v_lshl_add_u32 v2, v171, 8, v9
	v_lshl_add_u32 v6, v182, 8, v9
	v_lshl_add_u32 v11, v183, 8, v9
	v_lshl_add_u32 v12, v214, 8, v9
	v_mad_u32_u24 v215, v171, s92, v9
	v_bfe_u32 v14, v167, 2, 2
	v_cmp_lt_i32_e32 vcc, v22, v23
	v_lshl_add_u32 v23, v1, 8, v9
	v_lshlrev_b32_e32 v25, 4, v17
	v_bitop3_b32 v17, v171, v1, 12 bitop3:0x36
	v_add_u32_e32 v9, v9, v15
	v_or_b32_e32 v15, 32, v173
	v_or_b32_e32 v28, 7, v26
	v_med3_u32 v20, v172, 8, 56
	v_lshlrev_b32_e32 v27, 4, v17
	v_or_b32_e32 v17, v173, v14
	v_or_b32_e32 v14, v15, v14
	v_add_u32_e32 v21, -8, v20
	v_cmp_lt_u32_e64 s[10:11], 16, v28
	v_cmp_lt_u32_e64 s[12:13], 32, v28
	v_mul_u32_u24_e32 v28, 0x120, v14
	v_or_b32_e32 v14, 1, v173
	v_cmp_ge_u32_e64 s[16:17], v14, v21
	v_or_b32_e32 v14, 2, v173
	v_cmp_ge_u32_e64 s[18:19], v14, v21
	v_or_b32_e32 v14, 3, v173
	v_add_u32_e32 v20, 8, v20
	v_cmp_ge_u32_e64 s[20:21], v14, v21
	v_or_b32_e32 v14, 16, v173
	v_cndmask_b32_e32 v22, v191, v22, vcc
	v_cmp_ge_u32_e32 vcc, v14, v21
	v_cmp_lt_u32_e64 s[22:23], v14, v20
	v_or_b32_e32 v14, 17, v173
	s_and_b64 s[52:53], vcc, s[22:23]
	v_cmp_ge_u32_e32 vcc, v14, v21
	v_cmp_lt_u32_e64 s[22:23], v14, v20
	v_or_b32_e32 v14, 18, v173
	s_and_b64 s[94:95], vcc, s[22:23]
	v_cmp_ge_u32_e32 vcc, v14, v21
	v_cmp_lt_u32_e64 s[22:23], v14, v20
	v_or_b32_e32 v14, 19, v173
	s_and_b64 s[76:77], vcc, s[22:23]
	v_cmp_ge_u32_e32 vcc, v14, v21
	v_cmp_lt_u32_e64 s[22:23], v14, v20
	s_and_b64 s[60:61], vcc, s[22:23]
	v_cmp_ge_u32_e32 vcc, v15, v21
	v_cmp_lt_u32_e64 s[22:23], v15, v20
	v_or_b32_e32 v14, 33, v173
	s_and_b64 s[62:63], vcc, s[22:23]
	v_cmp_ge_u32_e32 vcc, v14, v21
	v_cmp_lt_u32_e64 s[22:23], v14, v20
	v_or_b32_e32 v14, 34, v173
	s_and_b64 s[68:69], vcc, s[22:23]
	v_cmp_ge_u32_e32 vcc, v14, v21
	v_cmp_lt_u32_e64 s[22:23], v14, v20
	v_or_b32_e32 v14, 35, v173
	v_lshlrev_b32_e32 v0, 3, v1
	v_lshlrev_b32_e32 v179, 2, v22
	v_bitop3_b32 v22, v171, v1, 3 bitop3:0x6c
	s_and_b64 s[92:93], vcc, s[22:23]
	v_cmp_ge_u32_e32 vcc, v14, v21
	v_cmp_lt_u32_e64 s[22:23], v14, v20
	v_or_b32_e32 v14, 48, v173
	v_add3_u32 v4, v4, v5, v10
	v_lshlrev_b32_e32 v1, 2, v1
	s_and_b64 s[96:97], vcc, s[22:23]
	v_cmp_lt_u32_e64 s[22:23], v14, v20
	v_or_b32_e32 v14, 49, v173
	v_sub_u32_e32 v1, v4, v1
	v_and_b32_e32 v4, 0xc0, v167
	s_mulk_i32 s30, 0x7c
	v_xor_b32_e32 v7, v171, v169
	v_lshlrev_b32_e32 v13, 4, v169
	v_cmp_lt_u32_e64 s[24:25], v14, v20
	v_or_b32_e32 v14, 50, v173
	v_sub_u32_e32 v1, v1, v4
	s_mulk_i32 s31, 0xf80
	v_bitop3_b32 v3, v171, v167, 15 bitop3:0x78
	v_lshlrev_b32_e32 v7, 4, v7
	v_and_b32_e32 v216, 0xf0, v13
	v_add_u32_e32 v18, 0x2400, v215
	v_add_u32_e32 v19, 0x3600, v215
	v_lshlrev_b32_e32 v22, 4, v22
	v_lshlrev_b32_e32 v24, 4, v24
	v_cmp_gt_u32_e64 s[6:7], 17, v26
	v_cmp_gt_u32_e64 s[8:9], 33, v26
	v_mul_u32_u24_e32 v26, 0x120, v17
	v_cmp_lt_u32_e64 s[26:27], v14, v20
	v_or_b32_e32 v14, 51, v173
	v_subrev_u32_e32 v1, s30, v1
	v_mov_b32_e32 v17, v16
	v_lshlrev_b32_e32 v3, 4, v3
	v_and_b32_e32 v7, 0xf0, v7
	v_add_u32_e32 v13, 0x1200, v215
	v_cmp_ge_u32_e64 s[14:15], v173, v21
	v_cmp_lt_u32_e64 s[28:29], v14, v20
	v_subrev_u32_e32 v1, s31, v1
	v_readlane_b32 s30, v255, 12
	v_mov_b32_e32 v14, v16
	v_mov_b32_e32 v15, v16
	v_add_u32_e32 v223, v18, v216
	v_add_u32_e32 v224, v19, v216
	v_add_u32_e32 v220, v23, v22
	v_add_u32_e32 v219, v23, v24
	v_add_u32_e32 v218, v23, v25
	v_add_u32_e32 v217, v23, v27
	v_add_u32_e32 v181, v9, v26
	v_add_u32_e32 v180, v9, v28
	v_mov_b64_e32 v[48:49], v[16:17]
	v_mov_b64_e32 v[44:45], v[16:17]
	v_mov_b64_e32 v[40:41], v[16:17]
	v_mov_b64_e32 v[36:37], v[16:17]
	v_mov_b64_e32 v[32:33], v[16:17]
	v_mov_b64_e32 v[28:29], v[16:17]
	v_mov_b64_e32 v[24:25], v[16:17]
	v_mov_b64_e32 v[20:21], v[16:17]
	v_cmp_gt_u32_e64 s[4:5], 64, v169
	s_mov_b32 s82, 0
	v_add_u32_e32 v221, s30, v1
	v_mov_b32_e32 v230, 0xf149f2ca
	v_mov_b32_e32 v229, 0
	v_lshlrev_b32_e32 v162, 1, v0
	v_lshlrev_b32_e32 v164, 1, v8
	v_add_u32_e32 v225, v2, v3
	v_add_u32_e32 v226, v6, v7
	v_add_u32_e32 v227, v11, v7
	v_add_u32_e32 v228, v12, v7
	v_add_u32_e32 v222, v13, v216
	v_mov_b64_e32 v[46:47], v[14:15]
	v_mov_b64_e32 v[42:43], v[14:15]
	v_mov_b64_e32 v[38:39], v[14:15]
	v_mov_b64_e32 v[34:35], v[14:15]
	v_mov_b64_e32 v[30:31], v[14:15]
	v_mov_b64_e32 v[26:27], v[14:15]
	v_mov_b64_e32 v[22:23], v[14:15]
	v_mov_b64_e32 v[18:19], v[14:15]
	s_nop 0

.LBB0_442:
	v_fma_f32 v0, v116, s65, -v115
	v_exp_f32_e32 v0, v0
	v_fma_f32 v1, v114, s65, -v115
	v_exp_f32_e32 v1, v1
	v_fma_f32 v2, v118, s65, -v115
	v_exp_f32_e32 v2, v2
	v_add_f32_e32 v3, 0, v0
	v_add_f32_e32 v3, v1, v3
	v_fma_f32 v4, v120, s65, -v115
	v_add_f32_e32 v7, v2, v3
	v_fma_f32 v3, v117, s65, -v115
	v_exp_f32_e32 v3, v3
	v_exp_f32_e32 v4, v4
	v_fma_f32 v5, v119, s65, -v115
	v_exp_f32_e32 v5, v5
	v_fma_f32 v6, v122, s65, -v115
	v_exp_f32_e32 v6, v6
	v_add_f32_e32 v7, v3, v7
	v_add_f32_e32 v7, v4, v7
	v_add_f32_e32 v7, v5, v7
	v_add_f32_e32 v11, v6, v7
	v_fma_f32 v7, v121, s65, -v115
	v_exp_f32_e32 v7, v7
	v_fma_f32 v8, v124, s65, -v115
	v_exp_f32_e32 v8, v8
	v_fma_f32 v9, v123, s65, -v115
	v_exp_f32_e32 v9, v9
	v_fma_f32 v10, v126, s65, -v115
	v_exp_f32_e32 v10, v10
	v_add_f32_e32 v11, v7, v11
	v_add_f32_e32 v11, v8, v11
	v_add_f32_e32 v11, v9, v11
	v_add_f32_e32 v15, v10, v11
	v_fma_f32 v11, v125, s65, -v115
	v_exp_f32_e32 v11, v11
	v_fma_f32 v12, v128, s65, -v115
	v_exp_f32_e32 v12, v12
	v_fma_f32 v13, v127, s65, -v115
	v_exp_f32_e32 v13, v13
	v_fma_f32 v14, v130, s65, -v115
	v_exp_f32_e32 v14, v14
	v_add_f32_e32 v15, v11, v15
	v_add_f32_e32 v15, v12, v15
	v_add_f32_e32 v15, v13, v15
	v_add_f32_e32 v131, v14, v15
	v_fma_f32 v15, v129, s65, -v115
	v_sub_f32_e32 v114, v230, v115
	v_exp_f32_e32 v114, v114
	s_andn2_b64 vcc, exec, s[72:73]
	s_cbranch_vccz .LBB0_438
	s_branch .LBB0_439
	s_nop 0
